# loop-edge edit: K-fragment LDS reads of each attention tile issued at the barrier release, ahead of prefetch address math and global-load issue (diff + mla, both unrolled copies)
# baseline (speedup 1.0000x reference)
; #define LAS __attribute__((address_space(3)))
; #define ATT_LOAD(S, j) do { rk##S = *(const u32x4*)(ksrc + (size_t)(j) * 64 * 1024); if (!DIFF && tid < 256) rk2##S = *(const u32x4*)(k2src + (size_t)(j) * 64 * 32); \
;         rv0##S = *(const u32x4*)(vsrc + (size_t)(j) * 64 * 1024); if (DIFF) rv1##S = *(const u32x4*)(vsrc + (size_t)(j) * 64 * 1024 + 32 * 1024); } while (0)
; #define ATT_COMPUTE(j, bufp) do { if ((j) < my_nt) { const int kb_ = 64 * (j); const int mode_ = DIFF ? ((kb_ + 63 - qrow0 <= -128) ? 1 : 2) : 0; \
;         attn_tile<DQK, DV, DIFF>(st, (bufp), (bufp) + KB, mode_, tab, kb_ - (qrow0 + q), 64, (j) == 0, wsf, lane); } } while (0)
; template <int DQK, int DV, bool HAS_BIAS>
; __device__ __forceinline__ void attn_tile(AttnState<DQK, DV>& st, const LAS unsigned char* Kt, const LAS unsigned char* Vt, int bias_mode, const LAS float* tab, int rel0, int nkeys, bool first, LAS float* wsf, int lane) {
;     ...
;     const LAS unsigned char* kp = Kt + q * PK + hi * 16;
;     bf16x8 ka[KS], kb[KS];
; #pragma unroll
;     for (int ks = 0; ks < KS; ++ks) { ka[ks] = *(const LAS bf16x8*)(kp + ks * 32); kb[ks] = *(const LAS bf16x8*)(kp + 32 * PK + ks * 32); }
; template <bool DIFF>
; __device__ __forceinline__ void attn_unit_coop(const Grp& G, int b, int h, int qb, int n, LAS unsigned char* lds, const int tid_in) {
;     ...
;         for (int j = 0; j < NT; j += 2) {
;             LAS unsigned char* b0 = tiles + (j & 1) * TB; LAS unsigned char* b1 = tiles + ((j + 1) & 1) * TB;
;             if (j + 2 < NT) ATT_LOAD(B, j + 2);
;             ATT_COMPUTE(j, b0);
.LBB0_520:
	ds_read_b128 v[180:183], v221 offset:8192
	ds_read_b128 v[160:163], v221 offset:8224
	ds_read_b128 v[176:179], v221 offset:12800
	ds_read_b128 v[164:167], v221 offset:12832
	ds_read_b128 v[156:159], v221 offset:8256
	ds_read_b128 v[152:155], v221 offset:8288
	ds_read_b128 v[172:175], v221 offset:12864
	ds_read_b128 v[168:171], v221 offset:12896
	s_add_i32 s69, s59, 2
	s_cmp_lt_u32 s69, s6
	s_cselect_b64 s[42:43], -1, 0
	s_cmp_ge_u32 s69, s6
	s_cselect_b64 s[40:41], -1, 0
	s_and_b64 vcc, exec, s[40:41]
	v_lshl_add_u64 v[200:201], v[196:197], 0, s[12:13]
	v_lshl_add_u64 v[202:203], v[198:199], 0, s[12:13]
	s_cbranch_vccnz .LBB0_522
	s_mov_b64 vcc, 0x10000
	v_lshl_add_u64 v[80:81], v[202:203], 0, s[96:97]
	global_load_dwordx4 v[140:143], v[80:81], off
	v_lshl_add_u64 v[80:81], v[200:201], 0, s[96:97]
	v_lshl_add_u64 v[82:83], v[80:81], 0, vcc
	global_load_dwordx4 v[144:147], v[80:81], off
	global_load_dwordx4 v[148:151], v[82:83], off
.LBB0_522:
	s_cmp_gt_i32 s59, s7
	s_cbranch_scc1 .LBB0_536
	s_add_i32 s2, s92, s58
	s_add_i32 s2, s2, 63
	s_cmpk_lt_i32 s2, 0xff81
	s_mov_b64 s[2:3], -1
	s_cbranch_scc0 .LBB0_525
	s_waitcnt vmcnt(6) lgkmcnt(7)
	v_mfma_f32_32x32x16_bf16 v[80:95], v[180:183], v[112:115], v[64:79]
	s_mov_b64 s[2:3], 0
	s_waitcnt lgkmcnt(5)
	v_mfma_f32_32x32x16_bf16 v[96:111], v[176:179], v[112:115], v[64:79]

; #define LAS __attribute__((address_space(3)))
; #define ATT_LOAD(S, j) do { rk##S = *(const u32x4*)(ksrc + (size_t)(j) * 64 * 1024); if (!DIFF && tid < 256) rk2##S = *(const u32x4*)(k2src + (size_t)(j) * 64 * 32); \
;         rv0##S = *(const u32x4*)(vsrc + (size_t)(j) * 64 * 1024); if (DIFF) rv1##S = *(const u32x4*)(vsrc + (size_t)(j) * 64 * 1024 + 32 * 1024); } while (0)
; #define ATT_STORE(S, bufp) do { *(LAS u32x4*)((bufp) + kdst) = rk##S; if (!DIFF && tid < 256) *(LAS u32x4*)((bufp) + k2dst) = rk2##S; \
;         *(LAS u32x4*)((bufp) + vdst) = rv0##S; if (DIFF) *(LAS u32x4*)((bufp) + vdst + 32 * PV) = rv1##S; } while (0)
; #define ATT_COMPUTE(j, bufp) do { if ((j) < my_nt) { const int kb_ = 64 * (j); const int mode_ = DIFF ? ((kb_ + 63 - qrow0 <= -128) ? 1 : 2) : 0; \
;         attn_tile<DQK, DV, DIFF>(st, (bufp), (bufp) + KB, mode_, tab, kb_ - (qrow0 + q), 64, (j) == 0, wsf, lane); } } while (0)
; template <int DQK, int DV, bool HAS_BIAS>
; __device__ __forceinline__ void attn_tile(AttnState<DQK, DV>& st, const LAS unsigned char* Kt, const LAS unsigned char* Vt, int bias_mode, const LAS float* tab, int rel0, int nkeys, bool first, LAS float* wsf, int lane) {
;     ...
;     const LAS unsigned char* kp = Kt + q * PK + hi * 16;
;     bf16x8 ka[KS], kb[KS];
; #pragma unroll
;     for (int ks = 0; ks < KS; ++ks) { ka[ks] = *(const LAS bf16x8*)(kp + ks * 32); kb[ks] = *(const LAS bf16x8*)(kp + 32 * PK + ks * 32); }
; template <bool DIFF>
; __device__ __forceinline__ void attn_unit_coop(const Grp& G, int b, int h, int qb, int n, LAS unsigned char* lds, const int tid_in) {
;     ...
;             ATT_STORE(A, b1);
;             __syncthreads();
;             if (j + 3 < NT) ATT_LOAD(A, j + 3);
;             ATT_COMPUTE(j + 1, b1);
.LBB0_536:
	s_add_i32 s2, s59, 3
	s_cmp_ge_u32 s2, s6
	s_waitcnt vmcnt(2)
	ds_write_b128 v214, v[128:131] offset:37888
	s_waitcnt vmcnt(1)
	ds_write_b128 v215, v[132:135] offset:47104
	s_waitcnt vmcnt(0)
	ds_write_b128 v215, v[136:139] offset:57344
	s_waitcnt lgkmcnt(0)
	s_barrier
	ds_read_b128 v[180:183], v221 offset:37888
	ds_read_b128 v[160:163], v221 offset:37920
	ds_read_b128 v[176:179], v221 offset:42496
	ds_read_b128 v[164:167], v221 offset:42528
	ds_read_b128 v[156:159], v221 offset:37952
	ds_read_b128 v[152:155], v221 offset:37984
	ds_read_b128 v[172:175], v221 offset:42560
	ds_read_b128 v[168:171], v221 offset:42592
	s_cbranch_scc0 .LBB0_542
	s_cmp_ge_i32 s59, s7
	s_cbranch_scc0 .LBB0_543

; __device__ __forceinline__ int crow(int r, int hi) { return (r & 3) + 8 * (r >> 2) + 4 * hi; }
; template <int DQK, int DV, bool HAS_BIAS>
; __device__ __forceinline__ void attn_tile(AttnState<DQK, DV>& st, const LAS unsigned char* Kt, const LAS unsigned char* Vt, int bias_mode, const LAS float* tab, int rel0, int nkeys, bool first, LAS float* wsf, int lane) {
;     ...
;     if (HAS_BIAS && bias_mode == 2) {
;         asm volatile("" ::: "memory");
; #pragma unroll
;         for (int r = 0; r < 16; ++r) {
;             const int k = crow(r, hi);
;             const int i0 = min(max(rel0 + k + 128, 0), 191), i1 = min(max(rel0 + k + 160, 0), 191);
;             p0[r] = tab[i0] + st.negm[r]; p1[r] = tab[i1] + st.negm[r];
;         }
;         p0 = __builtin_amdgcn_mfma_f32_32x32x16_bf16(ka[0], st.qf[0], p0, 0, 0, 0);
;         p1 = __builtin_amdgcn_mfma_f32_32x32x16_bf16(kb[0], st.qf[0], p1, 0, 0, 0);
;     } else {
;         p0 = __builtin_amdgcn_mfma_f32_32x32x16_bf16(ka[0], st.qf[0], st.negm, 0, 0, 0);
;         p1 = __builtin_amdgcn_mfma_f32_32x32x16_bf16(kb[0], st.qf[0], st.negm, 0, 0, 0);
.LBB0_543:
	s_add_i32 s2, s92, s58
	s_addk_i32 s2, 0x7f
	s_cmpk_lt_i32 s2, 0xff81
	s_mov_b64 s[2:3], -1
	s_cbranch_scc0 .LBB0_545
	s_waitcnt lgkmcnt(7)
	v_mfma_f32_32x32x16_bf16 v[80:95], v[180:183], v[112:115], v[64:79]
	s_mov_b64 s[2:3], 0
	s_waitcnt lgkmcnt(5)
	v_mfma_f32_32x32x16_bf16 v[96:111], v[176:179], v[112:115], v[64:79]

; #define LAS __attribute__((address_space(3)))
; #define ATT_LOAD(S, j) do { rk##S = *(const u32x4*)(ksrc + (size_t)(j) * 64 * 1024); if (!DIFF && tid < 256) rk2##S = *(const u32x4*)(k2src + (size_t)(j) * 64 * 32); \
;         rv0##S = *(const u32x4*)(vsrc + (size_t)(j) * 64 * 1024); if (DIFF) rv1##S = *(const u32x4*)(vsrc + (size_t)(j) * 64 * 1024 + 32 * 1024); } while (0)
; template <int DQK, int DV, bool HAS_BIAS>
; __device__ __forceinline__ void attn_tile(AttnState<DQK, DV>& st, const LAS unsigned char* Kt, const LAS unsigned char* Vt, int bias_mode, const LAS float* tab, int rel0, int nkeys, bool first, LAS float* wsf, int lane) {
;     ...
;     const LAS unsigned char* kp = Kt + q * PK + hi * 16;
;     bf16x8 ka[KS], kb[KS];
; #pragma unroll
;     for (int ks = 0; ks < KS; ++ks) { ka[ks] = *(const LAS bf16x8*)(kp + ks * 32); kb[ks] = *(const LAS bf16x8*)(kp + 32 * PK + ks * 32); }
; template <bool DIFF>
; __device__ __forceinline__ void attn_unit_coop(const Grp& G, int b, int h, int qb, int n, LAS unsigned char* lds, const int tid_in) {
;     ...
;         for (int j = 0; j < NT; j += 2) {
;             LAS unsigned char* b0 = tiles + (j & 1) * TB; LAS unsigned char* b1 = tiles + ((j + 1) & 1) * TB;
;             if (j + 2 < NT) ATT_LOAD(B, j + 2);
.LBB0_570:
	ds_read_b128 v[64:67], v162 offset:8192
	ds_read_b128 v[128:131], v162 offset:8224
	ds_read_b128 v[132:135], v162 offset:14848
	ds_read_b128 v[136:139], v162 offset:14880
	s_add_i32 s47, s58, 2
	s_cmp_lt_u32 s47, s7
	s_cselect_b64 s[36:37], -1, 0
	s_cmp_ge_u32 s47, s7
	s_cselect_b64 s[34:35], -1, 0
	s_and_b64 vcc, exec, s[34:35]
	v_lshl_add_u64 v[150:151], v[146:147], 0, s[10:11]
	s_cbranch_vccz .LBB0_577
	s_cmp_gt_i32 s58, s6
	s_cbranch_scc0 .LBB0_580

; #define LAS __attribute__((address_space(3)))
; #define ATT_LOAD(S, j) do { rk##S = *(const u32x4*)(ksrc + (size_t)(j) * 64 * 1024); if (!DIFF && tid < 256) rk2##S = *(const u32x4*)(k2src + (size_t)(j) * 64 * 32); \
;         rv0##S = *(const u32x4*)(vsrc + (size_t)(j) * 64 * 1024); if (DIFF) rv1##S = *(const u32x4*)(vsrc + (size_t)(j) * 64 * 1024 + 32 * 1024); } while (0)
; #define ATT_STORE(S, bufp) do { *(LAS u32x4*)((bufp) + kdst) = rk##S; if (!DIFF && tid < 256) *(LAS u32x4*)((bufp) + k2dst) = rk2##S; \
;         *(LAS u32x4*)((bufp) + vdst) = rv0##S; if (DIFF) *(LAS u32x4*)((bufp) + vdst + 32 * PV) = rv1##S; } while (0)
; #define ATT_COMPUTE(j, bufp) do { if ((j) < my_nt) { const int kb_ = 64 * (j); const int mode_ = DIFF ? ((kb_ + 63 - qrow0 <= -128) ? 1 : 2) : 0; \
;         attn_tile<DQK, DV, DIFF>(st, (bufp), (bufp) + KB, mode_, tab, kb_ - (qrow0 + q), 64, (j) == 0, wsf, lane); } } while (0)
; template <int DQK, int DV, bool HAS_BIAS>
; __device__ __forceinline__ void attn_tile(AttnState<DQK, DV>& st, const LAS unsigned char* Kt, const LAS unsigned char* Vt, int bias_mode, const LAS float* tab, int rel0, int nkeys, bool first, LAS float* wsf, int lane) {
;     ...
;     const LAS unsigned char* kp = Kt + q * PK + hi * 16;
;     bf16x8 ka[KS], kb[KS];
; #pragma unroll
;     for (int ks = 0; ks < KS; ++ks) { ka[ks] = *(const LAS bf16x8*)(kp + ks * 32); kb[ks] = *(const LAS bf16x8*)(kp + 32 * PK + ks * 32); }
; template <bool DIFF>
; __device__ __forceinline__ void attn_unit_coop(const Grp& G, int b, int h, int qb, int n, LAS unsigned char* lds, const int tid_in) {
;     ...
;             ATT_STORE(A, b1);
;             __syncthreads();
;             if (j + 3 < NT) ATT_LOAD(A, j + 3);
;             ATT_COMPUTE(j + 1, b1);
.LBB0_574:
	s_or_b64 exec, exec, s[4:5]
	s_add_i32 s4, s58, 3
	s_cmp_ge_u32 s4, s7
	s_waitcnt vmcnt(0)
	ds_write_b128 v157, v[112:115] offset:47104
	s_waitcnt lgkmcnt(0)
	s_barrier
	ds_read_b128 v[64:67], v162 offset:33792
	ds_read_b128 v[128:131], v162 offset:33824
	ds_read_b128 v[132:135], v162 offset:40448
	ds_read_b128 v[136:139], v162 offset:40480
	s_cbranch_scc0 .LBB0_582
	s_cmp_ge_i32 s58, s6
	s_cbranch_scc0 .LBB0_585

; #define LAS __attribute__((address_space(3)))
; template <int DQK, int DV, bool HAS_BIAS>
; __device__ __forceinline__ void attn_tile(AttnState<DQK, DV>& st, const LAS unsigned char* Kt, const LAS unsigned char* Vt, int bias_mode, const LAS float* tab, int rel0, int nkeys, bool first, LAS float* wsf, int lane) {
;     ...
;     const LAS unsigned char* kp = Kt + q * PK + hi * 16;
;     bf16x8 ka[KS], kb[KS];
; #pragma unroll
;     for (int ks = 0; ks < KS; ++ks) { ka[ks] = *(const LAS bf16x8*)(kp + ks * 32); kb[ks] = *(const LAS bf16x8*)(kp + 32 * PK + ks * 32); }
;     if (HAS_BIAS && bias_mode == 2) {
;         asm volatile("" ::: "memory");
; #pragma unroll
;         for (int r = 0; r < 16; ++r) {
;             const int k = crow(r, hi);
;             const int i0 = min(max(rel0 + k + 128, 0), 191), i1 = min(max(rel0 + k + 160, 0), 191);
;             p0[r] = tab[i0] + st.negm[r]; p1[r] = tab[i1] + st.negm[r];
;         }
;         p0 = __builtin_amdgcn_mfma_f32_32x32x16_bf16(ka[0], st.qf[0], p0, 0, 0, 0);
;         p1 = __builtin_amdgcn_mfma_f32_32x32x16_bf16(kb[0], st.qf[0], p1, 0, 0, 0);
;     } else {
;         p0 = __builtin_amdgcn_mfma_f32_32x32x16_bf16(ka[0], st.qf[0], st.negm, 0, 0, 0);
;         p1 = __builtin_amdgcn_mfma_f32_32x32x16_bf16(kb[0], st.qf[0], st.negm, 0, 0, 0);
;     }
; #pragma unroll
;     for (int ks = 1; ks < KS; ++ks) {
;         p0 = __builtin_amdgcn_mfma_f32_32x32x16_bf16(ka[ks], st.qf[ks], p0, 0, 0, 0);
;         p1 = __builtin_amdgcn_mfma_f32_32x32x16_bf16(kb[ks], st.qf[ks], p1, 0, 0, 0);
;     }
;     const int q4 = (lane & 15) >> 2, blk = (lane >> 4) & 1, pp = lane & 3;
;     const LAS unsigned char* vp = Vt + (4 * hi + q4) * PV + (16 * blk + 4 * pp) * 2;
;     s16x4 vlo[2][4], vhi[2][4];
; #pragma unroll
;     for (int s4 = 0; s4 < 4; ++s4) { vlo[0][s4] = vtr(vp + (16 * s4) * PV); vhi[0][s4] = vtr(vp + (16 * s4 + 8) * PV); }
;     __builtin_amdgcn_sched_barrier(0);
;     if (nkeys < 64) {
; #pragma unroll
;         for (int r = 0; r < 16; ++r) { const int k = crow(r, hi); if (k >= nkeys) p0[r] = -1e30f; if (k + 32 >= nkeys) p1[r] = -1e30f; }
;     }
;     float mxa = __builtin_fmaxf(__builtin_fmaxf(p0[0], p0[1]), p1[0]), mxb = __builtin_fmaxf(__builtin_fmaxf(p0[2], p0[3]), p1[1]);
;     mxa = __builtin_fmaxf(__builtin_fmaxf(mxa, p1[2]), p1[3]);
; #pragma unroll
;     for (int r = 4; r < 16; r += 4) {
.LBB0_580:
	s_cmp_eq_u32 s58, 0
	s_cselect_b64 s[4:5], -1, 0
	s_waitcnt lgkmcnt(3)
	v_mfma_f32_32x32x16_bf16 v[48:63], v[64:67], v[100:103], v[32:47]
	s_cmp_lg_u32 s58, 0
	s_waitcnt lgkmcnt(1)
	v_mfma_f32_32x32x16_bf16 v[64:79], v[132:135], v[100:103], v[32:47]
	v_mfma_f32_32x32x16_bf16 v[48:63], v[128:131], v[80:83], v[48:63]
	ds_read_b128 v[128:131], v162 offset:8256
	ds_read_b128 v[132:135], v162 offset:8288
	s_waitcnt lgkmcnt(2)
	v_mfma_f32_32x32x16_bf16 v[64:79], v[136:139], v[80:83], v[64:79]
	s_waitcnt lgkmcnt(1)
	v_mfma_f32_32x32x16_bf16 v[48:63], v[128:131], v[84:87], v[48:63]
	ds_read_b128 v[128:131], v162 offset:14912
	ds_read_b128 v[136:139], v162 offset:14944
	s_waitcnt lgkmcnt(1)
	v_mfma_f32_32x32x16_bf16 v[64:79], v[128:131], v[84:87], v[64:79]
	v_mfma_f32_32x32x16_bf16 v[48:63], v[132:135], v[88:91], v[48:63]
	ds_read_b128 v[128:131], v162 offset:8320
	ds_read_b128 v[132:135], v162 offset:8352
	s_waitcnt lgkmcnt(2)
	v_mfma_f32_32x32x16_bf16 v[64:79], v[136:139], v[88:91], v[64:79]
	s_waitcnt lgkmcnt(1)
	v_mfma_f32_32x32x16_bf16 v[48:63], v[128:131], v[92:95], v[48:63]
	ds_read_b128 v[128:131], v162 offset:14976
	ds_read_b128 v[164:167], v162 offset:15008
	s_waitcnt lgkmcnt(1)
	v_mfma_f32_32x32x16_bf16 v[64:79], v[128:131], v[92:95], v[64:79]
	v_mfma_f32_32x32x16_bf16 v[48:63], v[132:135], v[96:99], v[48:63]
	ds_read_b64_tr_b16 v[140:141], v163 offset:21504
	ds_read_b64_tr_b16 v[142:143], v163 offset:23040
	ds_read_b64_tr_b16 v[136:137], v163 offset:24576
	ds_read_b64_tr_b16 v[138:139], v163 offset:26112
	ds_read_b64_tr_b16 v[132:133], v163 offset:27648
	ds_read_b64_tr_b16 v[134:135], v163 offset:29184
	ds_read_b64_tr_b16 v[128:129], v163 offset:30720
	ds_read_b64_tr_b16 v[130:131], v163 offset:32256
	s_waitcnt lgkmcnt(8)
	v_mfma_f32_32x32x16_bf16 v[64:79], v[164:167], v[96:99], v[64:79]
	s_nop 1
	v_max_f32_e32 v152, v49, v49
	v_max_f32_e32 v164, v48, v48
	v_max_f32_e32 v152, v164, v152
	s_nop 6
	v_max3_f32 v164, v50, v51, v65
	v_max3_f32 v152, v152, v64, v66
	v_max3_f32 v152, v152, v67, v52
	v_max3_f32 v164, v164, v54, v55
	v_max3_f32 v152, v152, v53, v68
	v_max3_f32 v164, v164, v70, v71
	v_max3_f32 v152, v152, v69, v56
	v_max3_f32 v164, v164, v58, v59
	v_max3_f32 v152, v152, v57, v72
	v_max3_f32 v164, v164, v74, v75
	v_max3_f32 v152, v152, v73, v60
	v_max3_f32 v164, v164, v62, v63
	v_max3_f32 v152, v152, v61, v76
	v_max3_f32 v164, v164, v78, v79
	v_max3_f32 v152, v152, v77, v164
	v_mov_b32_e32 v164, v152
	s_nop 1
	v_permlane32_swap_b32_e32 v152, v164
	v_max_f32_e32 v164, v164, v164
	v_max_f32_e32 v152, v152, v152
	v_max_f32_e32 v152, v152, v164
	s_cbranch_scc0 .LBB0_595
	v_cmp_lt_f32_e32 vcc, s77, v152
	s_cmp_lg_u64 vcc, 0
	s_cselect_b64 s[38:39], -1, 0
	s_cbranch_execz .LBB0_596
	s_branch .LBB0_597

; #define LAS __attribute__((address_space(3)))
; template <int DQK, int DV, bool HAS_BIAS>
; __device__ __forceinline__ void attn_tile(AttnState<DQK, DV>& st, const LAS unsigned char* Kt, const LAS unsigned char* Vt, int bias_mode, const LAS float* tab, int rel0, int nkeys, bool first, LAS float* wsf, int lane) {
;     ...
;     const LAS unsigned char* kp = Kt + q * PK + hi * 16;
;     bf16x8 ka[KS], kb[KS];
; #pragma unroll
;     for (int ks = 0; ks < KS; ++ks) { ka[ks] = *(const LAS bf16x8*)(kp + ks * 32); kb[ks] = *(const LAS bf16x8*)(kp + 32 * PK + ks * 32); }
;     if (HAS_BIAS && bias_mode == 2) {
;         asm volatile("" ::: "memory");
; #pragma unroll
;         for (int r = 0; r < 16; ++r) {
;             const int k = crow(r, hi);
;             const int i0 = min(max(rel0 + k + 128, 0), 191), i1 = min(max(rel0 + k + 160, 0), 191);
;             p0[r] = tab[i0] + st.negm[r]; p1[r] = tab[i1] + st.negm[r];
;         }
;         p0 = __builtin_amdgcn_mfma_f32_32x32x16_bf16(ka[0], st.qf[0], p0, 0, 0, 0);
;         p1 = __builtin_amdgcn_mfma_f32_32x32x16_bf16(kb[0], st.qf[0], p1, 0, 0, 0);
;     } else {
;         p0 = __builtin_amdgcn_mfma_f32_32x32x16_bf16(ka[0], st.qf[0], st.negm, 0, 0, 0);
;         p1 = __builtin_amdgcn_mfma_f32_32x32x16_bf16(kb[0], st.qf[0], st.negm, 0, 0, 0);
;     }
; #pragma unroll
;     for (int ks = 1; ks < KS; ++ks) {
;         p0 = __builtin_amdgcn_mfma_f32_32x32x16_bf16(ka[ks], st.qf[ks], p0, 0, 0, 0);
;         p1 = __builtin_amdgcn_mfma_f32_32x32x16_bf16(kb[ks], st.qf[ks], p1, 0, 0, 0);
;     }
;     const int q4 = (lane & 15) >> 2, blk = (lane >> 4) & 1, pp = lane & 3;
;     const LAS unsigned char* vp = Vt + (4 * hi + q4) * PV + (16 * blk + 4 * pp) * 2;
;     s16x4 vlo[2][4], vhi[2][4];
; #pragma unroll
;     for (int s4 = 0; s4 < 4; ++s4) { vlo[0][s4] = vtr(vp + (16 * s4) * PV); vhi[0][s4] = vtr(vp + (16 * s4 + 8) * PV); }
;     __builtin_amdgcn_sched_barrier(0);
;     if (nkeys < 64) {
; #pragma unroll
;         for (int r = 0; r < 16; ++r) { const int k = crow(r, hi); if (k >= nkeys) p0[r] = -1e30f; if (k + 32 >= nkeys) p1[r] = -1e30f; }
;     }
;     float mxa = __builtin_fmaxf(__builtin_fmaxf(p0[0], p0[1]), p1[0]), mxb = __builtin_fmaxf(__builtin_fmaxf(p0[2], p0[3]), p1[1]);
;     mxa = __builtin_fmaxf(__builtin_fmaxf(mxa, p1[2]), p1[3]);
; #pragma unroll
;     for (int r = 4; r < 16; r += 4) {
.LBB0_585:
	s_waitcnt lgkmcnt(3)
	v_mfma_f32_32x32x16_bf16 v[48:63], v[64:67], v[100:103], v[32:47]
	s_waitcnt lgkmcnt(1)
	v_mfma_f32_32x32x16_bf16 v[64:79], v[132:135], v[100:103], v[32:47]
	v_mfma_f32_32x32x16_bf16 v[48:63], v[128:131], v[80:83], v[48:63]
	ds_read_b128 v[128:131], v162 offset:33856
	ds_read_b128 v[132:135], v162 offset:33888
	s_waitcnt lgkmcnt(2)
	v_mfma_f32_32x32x16_bf16 v[64:79], v[136:139], v[80:83], v[64:79]
	s_waitcnt lgkmcnt(1)
	v_mfma_f32_32x32x16_bf16 v[48:63], v[128:131], v[84:87], v[48:63]
	ds_read_b128 v[128:131], v162 offset:40512
	ds_read_b128 v[136:139], v162 offset:40544
	s_waitcnt lgkmcnt(1)
	v_mfma_f32_32x32x16_bf16 v[64:79], v[128:131], v[84:87], v[64:79]
	v_mfma_f32_32x32x16_bf16 v[48:63], v[132:135], v[88:91], v[48:63]
	ds_read_b128 v[128:131], v162 offset:33920
	ds_read_b128 v[132:135], v162 offset:33952
	s_waitcnt lgkmcnt(2)
	v_mfma_f32_32x32x16_bf16 v[64:79], v[136:139], v[88:91], v[64:79]
	s_waitcnt lgkmcnt(1)
	v_mfma_f32_32x32x16_bf16 v[48:63], v[128:131], v[92:95], v[48:63]
	ds_read_b128 v[128:131], v162 offset:40576
	ds_read_b128 v[164:167], v162 offset:40608
	s_waitcnt lgkmcnt(1)
	v_mfma_f32_32x32x16_bf16 v[64:79], v[128:131], v[92:95], v[64:79]
	v_mfma_f32_32x32x16_bf16 v[48:63], v[132:135], v[96:99], v[48:63]
	ds_read_b64_tr_b16 v[140:141], v163 offset:47104
	ds_read_b64_tr_b16 v[142:143], v163 offset:48640
	ds_read_b64_tr_b16 v[136:137], v163 offset:50176
	ds_read_b64_tr_b16 v[138:139], v163 offset:51712
	ds_read_b64_tr_b16 v[132:133], v163 offset:53248
	ds_read_b64_tr_b16 v[134:135], v163 offset:54784
	ds_read_b64_tr_b16 v[128:129], v163 offset:56320
	ds_read_b64_tr_b16 v[130:131], v163 offset:57856
	s_waitcnt lgkmcnt(8)
	v_mfma_f32_32x32x16_bf16 v[64:79], v[164:167], v[96:99], v[64:79]
	s_nop 1
	v_max_f32_e32 v150, v49, v49
	v_max_f32_e32 v151, v48, v48
	v_max_f32_e32 v150, v151, v150
	s_nop 6
	v_max3_f32 v151, v50, v51, v65
	v_max3_f32 v150, v150, v64, v66
	v_max3_f32 v150, v150, v67, v52
	v_max3_f32 v151, v151, v54, v55
	v_max3_f32 v150, v150, v53, v68
	v_max3_f32 v151, v151, v70, v71
	v_max3_f32 v150, v150, v69, v56
	v_max3_f32 v151, v151, v58, v59
	v_max3_f32 v150, v150, v57, v72
	v_max3_f32 v151, v151, v74, v75
	v_max3_f32 v150, v150, v73, v60
	v_max3_f32 v151, v151, v62, v63
	v_max3_f32 v150, v150, v61, v76
	v_max3_f32 v151, v151, v78, v79
	v_max3_f32 v150, v150, v77, v151
	v_mov_b32_e32 v151, v150
	s_nop 1
	v_permlane32_swap_b32_e32 v150, v151
	v_max_f32_e32 v151, v151, v151
	v_max_f32_e32 v150, v150, v150
	v_max_f32_e32 v150, v150, v151
	v_cmp_lt_f32_e32 vcc, s77, v150
	s_cbranch_vccz .LBB0_589
	v_max_f32_e32 v32, v150, v150
	v_max_f32_e32 v150, 0, v32
	v_exp_f32_e64 v151, -v150
	s_and_saveexec_b64 s[4:5], s[2:3]
	ds_write_b32 v158, v151 offset:6144
	s_or_b64 exec, exec, s[4:5]
	ds_read_b128 v[164:167], v155 offset:6144
	ds_read_b128 v[168:171], v155 offset:6176
	ds_read_b128 v[172:175], v155 offset:6208
	ds_read_b128 v[176:179], v155 offset:6240
	v_add_f32_e32 v161, v161, v150
	v_xor_b32_e32 v32, 0x80000000, v161
	v_pk_add_f32 v[48:49], v[48:49], v[150:151] op_sel_hi:[1,0] neg_lo:[0,1] neg_hi:[0,1]
	v_pk_add_f32 v[64:65], v[64:65], v[150:151] op_sel_hi:[1,0] neg_lo:[0,1] neg_hi:[0,1]
	v_pk_add_f32 v[50:51], v[50:51], v[150:151] op_sel_hi:[1,0] neg_lo:[0,1] neg_hi:[0,1]
	v_pk_add_f32 v[66:67], v[66:67], v[150:151] op_sel_hi:[1,0] neg_lo:[0,1] neg_hi:[0,1]
	v_pk_add_f32 v[52:53], v[52:53], v[150:151] op_sel_hi:[1,0] neg_lo:[0,1] neg_hi:[0,1]
	v_pk_add_f32 v[68:69], v[68:69], v[150:151] op_sel_hi:[1,0] neg_lo:[0,1] neg_hi:[0,1]
	v_pk_add_f32 v[54:55], v[54:55], v[150:151] op_sel_hi:[1,0] neg_lo:[0,1] neg_hi:[0,1]
	v_pk_add_f32 v[70:71], v[70:71], v[150:151] op_sel_hi:[1,0] neg_lo:[0,1] neg_hi:[0,1]
	v_pk_add_f32 v[56:57], v[56:57], v[150:151] op_sel_hi:[1,0] neg_lo:[0,1] neg_hi:[0,1]
	v_pk_add_f32 v[72:73], v[72:73], v[150:151] op_sel_hi:[1,0] neg_lo:[0,1] neg_hi:[0,1]
	v_pk_add_f32 v[58:59], v[58:59], v[150:151] op_sel_hi:[1,0] neg_lo:[0,1] neg_hi:[0,1]
	v_pk_add_f32 v[74:75], v[74:75], v[150:151] op_sel_hi:[1,0] neg_lo:[0,1] neg_hi:[0,1]
	v_pk_add_f32 v[60:61], v[60:61], v[150:151] op_sel_hi:[1,0] neg_lo:[0,1] neg_hi:[0,1]
	v_pk_add_f32 v[76:77], v[76:77], v[150:151] op_sel_hi:[1,0] neg_lo:[0,1] neg_hi:[0,1]
	v_mov_b32_e32 v33, v32
	v_mov_b32_e32 v34, v32
	v_mov_b32_e32 v35, v32
	v_mov_b32_e32 v36, v32
	v_mov_b32_e32 v37, v32
	v_mov_b32_e32 v38, v32
	v_mov_b32_e32 v39, v32
	v_mov_b32_e32 v40, v32
	v_mov_b32_e32 v41, v32
	v_mov_b32_e32 v42, v32
	v_mov_b32_e32 v43, v32
	v_mov_b32_e32 v44, v32
	v_mov_b32_e32 v45, v32
	v_mov_b32_e32 v46, v32
	v_mov_b32_e32 v47, v32
	v_pk_add_f32 v[62:63], v[62:63], v[150:151] op_sel_hi:[1,0] neg_lo:[0,1] neg_hi:[0,1]
	v_pk_add_f32 v[78:79], v[78:79], v[150:151] op_sel_hi:[1,0] neg_lo:[0,1] neg_hi:[0,1]
	v_mul_f32_e32 v160, v160, v151
	s_waitcnt lgkmcnt(0)
	v_pk_mul_f32 v[30:31], v[30:31], v[178:179]
	v_pk_mul_f32 v[26:27], v[26:27], v[174:175]
	v_pk_mul_f32 v[22:23], v[22:23], v[170:171]
	v_pk_mul_f32 v[18:19], v[18:19], v[166:167]
	v_pk_mul_f32 v[28:29], v[28:29], v[176:177]
	v_pk_mul_f32 v[24:25], v[24:25], v[172:173]
	v_pk_mul_f32 v[20:21], v[20:21], v[168:169]
	v_pk_mul_f32 v[16:17], v[16:17], v[164:165]
	v_pk_mul_f32 v[14:15], v[14:15], v[178:179]
	v_pk_mul_f32 v[10:11], v[10:11], v[174:175]
	v_pk_mul_f32 v[6:7], v[6:7], v[170:171]
	v_pk_mul_f32 v[2:3], v[2:3], v[166:167]
	v_pk_mul_f32 v[12:13], v[12:13], v[176:177]
	v_pk_mul_f32 v[8:9], v[8:9], v[172:173]
	v_pk_mul_f32 v[4:5], v[4:5], v[168:169]
	v_pk_mul_f32 v[0:1], v[0:1], v[164:165]
